# mixer-in GEMM epilogue: the 8 row-statistic loads issued together instead of 5 serialized load/wait round trips
# speedup vs baseline: 1.0044x; 1.0044x over previous
; __device__ __forceinline__ unsigned cvt_pk_bf16(float lo, float hi) { unsigned r; asm volatile("v_cvt_pk_bf16_f32 %0, %1, %2" : "=v"(r) : "v"(lo), "v"(hi)); return r; }
; __device__ __forceinline__ float ssq_rs(ssq_t v) { return __builtin_amdgcn_rsqf((float)v * (1.0f / (16777216.0f * 1024.0f)) + RMS_EPS); }
;     __device__ __forceinline__ void operator()(const f32x4 (&acc)[2][2][4][2], const Unit& u, int wr, int wc, int fr, int fq) const {
;         const int row0 = u.pm * BM + wr * 64 + fr, col0 = u.pn * BM + wc * 32 + 8 * fq;
;         float rsv[2][4];
; #pragma unroll
;         for (int ai = 0; ai < 2; ++ai)
; #pragma unroll
;             for (int m = 0; m < 4; ++m) rsv[ai][m] = ssq ? ssq_rs(ssq[row0 + ai * HALF + m * 16]) : 1.0f;
;         asm volatile("" ::: "memory");
; #pragma unroll
;         for (int ai = 0; ai < 2; ++ai)
; #pragma unroll
;             for (int m = 0; m < 4; ++m) {
;                 const int row = row0 + ai * HALF + m * 16;
;                 const float rs = rsv[ai][m];
;                 bf16_t* rowp = O + (size_t)row * ldc + col0;
; #pragma unroll
;                 for (int bj = 0; bj < 2; ++bj) {
;                     const f32x4 v0 = acc[ai][bj][m][0] * rs, v1 = acc[ai][bj][m][1] * rs;
;                     u32x4 w; w.x = cvt_pk_bf16(v0[0], v0[1]); w.y = cvt_pk_bf16(v0[2], v0[3]); w.z = cvt_pk_bf16(v1[0], v1[1]); w.w = cvt_pk_bf16(v1[2], v1[3]);
;                     *(u32x4*)(rowp + bj * HALF) = w;
.LBB0_379:
	v_lshl_add_u32 v138, s50, 8, v141
	v_ashrrev_i32_e32 v139, 31, v138
	v_lshl_add_u64 v[142:143], v[138:139], 3, s[0:1]
	global_load_dwordx2 v[238:239], v[142:143], off
	global_load_dwordx2 v[240:241], v[142:143], off offset:384
	global_load_dwordx2 v[242:243], v[142:143], off offset:128
	global_load_dwordx2 v[244:245], v[142:143], off offset:256
	global_load_dwordx2 v[246:247], v[142:143], off offset:1024
	global_load_dwordx2 v[248:249], v[142:143], off offset:1152
	global_load_dwordx2 v[250:251], v[142:143], off offset:1280
	global_load_dwordx2 v[228:229], v[142:143], off offset:1408
	v_mad_i64_i32 v[158:159], s[6:7], v138, s26, 0
	v_lshl_add_u64 v[158:159], v[158:159], 1, s[62:63]
	v_readlane_b32 s72, v255, 12
	s_mov_b64 s[46:47], -1
	s_andn2_b64 vcc, exec, s[36:37]
	v_readlane_b32 s73, v255, 13
	v_readlane_b32 s74, v255, 14
	v_readlane_b32 s75, v255, 15
	v_readlane_b32 s76, v255, 16
	v_readlane_b32 s77, v255, 17
	v_readlane_b32 s78, v255, 18
	v_readlane_b32 s79, v255, 19
	v_readlane_b32 s80, v255, 20
	v_readlane_b32 s81, v255, 21
	v_readlane_b32 s82, v255, 22
	v_readlane_b32 s83, v255, 23
	v_readlane_b32 s84, v255, 24
	v_readlane_b32 s85, v255, 25
	v_readlane_b32 s86, v255, 26
	v_readlane_b32 s87, v255, 27
	s_waitcnt vmcnt(0)
	v_mov_b32_e32 v150, v238
	v_mov_b32_e32 v151, v239
	v_mov_b32_e32 v156, v240
	v_mov_b32_e32 v157, v241
	v_ffbh_u32_e32 v139, v151
	v_min_u32_e32 v139, 32, v139
	v_lshlrev_b64 v[150:151], v139, v[150:151]
	v_min_u32_e32 v140, 1, v150
	v_or_b32_e32 v140, v151, v140
	v_mov_b32_e32 v150, v242
	v_mov_b32_e32 v151, v243
	v_cvt_f32_u32_e32 v140, v140
	v_sub_u32_e32 v139, 32, v139
	v_ldexp_f32 v139, v140, v139
	v_fmamk_f32 v139, v139, 0x2e800000, v193
	v_rsq_f32_e32 v154, v139
	s_waitcnt vmcnt(0)
	v_ffbh_u32_e32 v139, v151
	v_min_u32_e32 v139, 32, v139
	v_lshlrev_b64 v[150:151], v139, v[150:151]
	v_min_u32_e32 v140, 1, v150
	v_or_b32_e32 v140, v151, v140
	v_mov_b32_e32 v150, v244
	v_mov_b32_e32 v151, v245
	v_cvt_f32_u32_e32 v140, v140
	v_sub_u32_e32 v139, 32, v139
	v_pk_mul_f32 v[126:127], v[126:127], v[154:155] op_sel_hi:[1,0]
	v_pk_mul_f32 v[124:125], v[124:125], v[154:155] op_sel_hi:[1,0]
	v_ldexp_f32 v139, v140, v139
	v_fmamk_f32 v139, v139, 0x2e800000, v193
	v_rsq_f32_e32 v152, v139
	v_pk_mul_f32 v[160:161], v[122:123], v[154:155] op_sel_hi:[1,0]
	v_pk_mul_f32 v[122:123], v[120:121], v[154:155] op_sel_hi:[1,0]
	v_pk_mul_f32 v[116:117], v[116:117], v[154:155] op_sel_hi:[1,0]
	v_pk_mul_f32 v[118:119], v[118:119], v[154:155] op_sel_hi:[1,0]
	s_waitcnt vmcnt(0)
	v_ffbh_u32_e32 v139, v151
	v_min_u32_e32 v139, 32, v139
	v_lshlrev_b64 v[150:151], v139, v[150:151]
	v_min_u32_e32 v140, 1, v150
	v_or_b32_e32 v140, v151, v140
	v_cvt_f32_u32_e32 v140, v140
	v_sub_u32_e32 v139, 32, v139
	v_add_u32_e32 v151, 0x80, v138
	v_ldexp_f32 v139, v140, v139
	v_fmamk_f32 v139, v139, 0x2e800000, v193
	v_rsq_f32_e32 v150, v139
	v_ffbh_u32_e32 v139, v157
	v_min_u32_e32 v139, 32, v139
	v_lshlrev_b64 v[156:157], v139, v[156:157]
	v_min_u32_e32 v140, 1, v156
	v_or_b32_e32 v140, v157, v140
	v_mov_b32_e32 v156, v246
	v_mov_b32_e32 v157, v247
	v_cvt_f32_u32_e32 v140, v140
	v_sub_u32_e32 v139, 32, v139
	v_pk_mul_f32 v[96:97], v[96:97], v[150:151] op_sel_hi:[1,0]
	v_pk_mul_f32 v[84:85], v[84:85], v[150:151] op_sel_hi:[1,0]
	v_ldexp_f32 v139, v140, v139
	v_fmamk_f32 v139, v139, 0x2e800000, v193
	v_rsq_f32_e32 v146, v139
	v_pk_mul_f32 v[86:87], v[86:87], v[150:151] op_sel_hi:[1,0]
	v_pk_mul_f32 v[80:81], v[80:81], v[146:147] op_sel_hi:[1,0]
	v_pk_mul_f32 v[70:71], v[70:71], v[146:147] op_sel_hi:[1,0]
	v_pk_mul_f32 v[68:69], v[68:69], v[146:147] op_sel_hi:[1,0]
	s_waitcnt vmcnt(0)
	v_ffbh_u32_e32 v139, v157
	v_min_u32_e32 v139, 32, v139
	v_lshlrev_b64 v[156:157], v139, v[156:157]
	v_min_u32_e32 v140, 1, v156
	v_or_b32_e32 v140, v157, v140
	v_mov_b32_e32 v156, v248
	v_mov_b32_e32 v157, v249
	v_cvt_f32_u32_e32 v140, v140
	v_sub_u32_e32 v139, 32, v139
	v_ldexp_f32 v139, v140, v139
	v_fmamk_f32 v139, v139, 0x2e800000, v193
	v_rsq_f32_e32 v148, v139
	s_waitcnt vmcnt(0)
	v_ffbh_u32_e32 v139, v157
	v_min_u32_e32 v139, 32, v139
	v_lshlrev_b64 v[156:157], v139, v[156:157]
	v_min_u32_e32 v140, 1, v156
	v_or_b32_e32 v140, v157, v140
	v_mov_b32_e32 v156, v250
	v_mov_b32_e32 v157, v251
	v_cvt_f32_u32_e32 v140, v140
	v_mov_b32_e32 v142, v228
	v_mov_b32_e32 v143, v229
	v_sub_u32_e32 v139, 32, v139
	v_ldexp_f32 v139, v140, v139
	v_fmamk_f32 v139, v139, 0x2e800000, v193
	v_rsq_f32_e32 v144, v139
	v_cvt_pk_bf16_f32 v120, v124, v125
	v_cvt_pk_bf16_f32 v121, v126, v127
	v_cvt_pk_bf16_f32 v122, v122, v123
	v_cvt_pk_bf16_f32 v123, v160, v161
	v_pk_mul_f32 v[62:63], v[62:63], v[148:149] op_sel_hi:[1,0]
	v_pk_mul_f32 v[60:61], v[60:61], v[148:149] op_sel_hi:[1,0]
	v_pk_mul_f32 v[52:53], v[52:53], v[148:149] op_sel_hi:[1,0]
	v_pk_mul_f32 v[54:55], v[54:55], v[148:149] op_sel_hi:[1,0]
	v_pk_mul_f32 v[48:49], v[48:49], v[144:145] op_sel_hi:[1,0]
	v_pk_mul_f32 v[36:37], v[36:37], v[144:145] op_sel_hi:[1,0]
	v_pk_mul_f32 v[38:39], v[38:39], v[144:145] op_sel_hi:[1,0]
	s_waitcnt vmcnt(1)
	v_ffbh_u32_e32 v139, v157
	v_min_u32_e32 v139, 32, v139
	v_lshlrev_b64 v[156:157], v139, v[156:157]
	v_min_u32_e32 v140, 1, v156
	v_lshl_or_b32 v156, s48, 8, v147
	v_or_b32_e32 v140, v157, v140
	v_ashrrev_i32_e32 v157, 31, v156
	v_lshlrev_b64 v[156:157], 1, v[156:157]
	v_lshl_add_u64 v[158:159], v[158:159], 0, v[156:157]
	global_store_dwordx4 v[158:159], v[120:123], off
	s_waitcnt vmcnt(1)
; __device__ __forceinline__ unsigned cvt_pk_bf16(float lo, float hi) { unsigned r; asm volatile("v_cvt_pk_bf16_f32 %0, %1, %2" : "=v"(r) : "v"(lo), "v"(hi)); return r; }
;     __device__ __forceinline__ void operator()(const f32x4 (&acc)[2][2][4][2], const Unit& u, int wr, int wc, int fr, int fq) const {
;     ...
;         for (int ai = 0; ai < 2; ++ai)
; #pragma unroll
;             for (int m = 0; m < 4; ++m) {
;                 const int row = row0 + ai * HALF + m * 16;
;                 const float rs = rsv[ai][m];
;                 bf16_t* rowp = O + (size_t)row * ldc + col0;
; #pragma unroll
;                 for (int bj = 0; bj < 2; ++bj) {
;                     const f32x4 v0 = acc[ai][bj][m][0] * rs, v1 = acc[ai][bj][m][1] * rs;
;                     u32x4 w; w.x = cvt_pk_bf16(v0[0], v0[1]); w.y = cvt_pk_bf16(v0[2], v0[3]); w.z = cvt_pk_bf16(v1[0], v1[1]); w.w = cvt_pk_bf16(v1[2], v1[3]);
;                     *(u32x4*)(rowp + bj * HALF) = w;
;                 }
;             }
	v_ffbh_u32_e32 v153, v143
	v_min_u32_e32 v153, 32, v153
	v_pk_mul_f32 v[120:121], v[110:111], v[154:155] op_sel_hi:[1,0]
	v_pk_mul_f32 v[110:111], v[108:109], v[154:155] op_sel_hi:[1,0]
	v_cvt_pk_bf16_f32 v108, v116, v117
	v_cvt_pk_bf16_f32 v109, v118, v119
	v_pk_mul_f32 v[112:113], v[112:113], v[152:153] op_sel_hi:[1,0]
	v_cvt_pk_bf16_f32 v110, v110, v111
	v_cvt_pk_bf16_f32 v111, v120, v121
	global_store_dwordx4 v[158:159], v[108:111], off offset:256
	v_pk_mul_f32 v[100:101], v[100:101], v[152:153] op_sel_hi:[1,0]
	v_pk_mul_f32 v[102:103], v[102:103], v[152:153] op_sel_hi:[1,0]
	v_or_b32_e32 v108, 16, v138
	v_mad_i64_i32 v[108:109], s[6:7], v108, s26, 0
	v_lshl_add_u64 v[108:109], v[108:109], 1, s[62:63]
	v_lshl_add_u64 v[108:109], v[108:109], 0, v[156:157]
	v_pk_mul_f32 v[110:111], v[114:115], v[152:153] op_sel_hi:[1,0]
	v_pk_mul_f32 v[114:115], v[106:107], v[152:153] op_sel_hi:[1,0]
	v_pk_mul_f32 v[106:107], v[104:105], v[152:153] op_sel_hi:[1,0]
	v_cvt_pk_bf16_f32 v104, v112, v113
	v_cvt_pk_bf16_f32 v105, v110, v111
	v_cvt_f32_u32_e32 v140, v140
	v_cvt_pk_bf16_f32 v106, v106, v107
	v_cvt_pk_bf16_f32 v107, v114, v115
	global_store_dwordx4 v[108:109], v[104:107], off
	v_lshlrev_b64 v[142:143], v153, v[142:143]
	v_min_u32_e32 v142, 1, v142
	v_pk_mul_f32 v[104:105], v[94:95], v[152:153] op_sel_hi:[1,0]
	v_pk_mul_f32 v[94:95], v[92:93], v[152:153] op_sel_hi:[1,0]
	v_cvt_pk_bf16_f32 v92, v100, v101
	v_cvt_pk_bf16_f32 v93, v102, v103
	v_sub_u32_e32 v139, 32, v139
	v_cvt_pk_bf16_f32 v94, v94, v95
	v_cvt_pk_bf16_f32 v95, v104, v105
	global_store_dwordx4 v[108:109], v[92:95], off offset:256
	v_or_b32_e32 v142, v143, v142
	v_ldexp_f32 v139, v140, v139
	v_or_b32_e32 v92, 32, v138
	v_mad_i64_i32 v[92:93], s[6:7], v92, s26, 0
	v_lshl_add_u64 v[92:93], v[92:93], 1, s[62:63]
	v_lshl_add_u64 v[92:93], v[92:93], 0, v[156:157]
	v_pk_mul_f32 v[94:95], v[98:99], v[150:151] op_sel_hi:[1,0]
	v_pk_mul_f32 v[98:99], v[90:91], v[150:151] op_sel_hi:[1,0]
	v_pk_mul_f32 v[90:91], v[88:89], v[150:151] op_sel_hi:[1,0]
	v_cvt_pk_bf16_f32 v88, v96, v97
	v_cvt_pk_bf16_f32 v89, v94, v95
	v_cvt_f32_u32_e32 v142, v142
	v_cvt_pk_bf16_f32 v90, v90, v91
	v_cvt_pk_bf16_f32 v91, v98, v99
	global_store_dwordx4 v[92:93], v[88:91], off
	v_fmamk_f32 v139, v139, 0x2e800000, v193
	v_rsq_f32_e32 v140, v139
	v_pk_mul_f32 v[88:89], v[78:79], v[150:151] op_sel_hi:[1,0]
	v_pk_mul_f32 v[78:79], v[76:77], v[150:151] op_sel_hi:[1,0]
	v_cvt_pk_bf16_f32 v76, v84, v85
	v_cvt_pk_bf16_f32 v77, v86, v87
	v_sub_u32_e32 v143, 32, v153
	v_cvt_pk_bf16_f32 v78, v78, v79
	v_cvt_pk_bf16_f32 v79, v88, v89
	global_store_dwordx4 v[92:93], v[76:79], off offset:256
	v_ldexp_f32 v142, v142, v143
	v_fmamk_f32 v142, v142, 0x2e800000, v193
	v_or_b32_e32 v76, 48, v138
	v_mad_i64_i32 v[76:77], s[6:7], v76, s26, 0
	v_lshl_add_u64 v[76:77], v[76:77], 1, s[62:63]
	v_lshl_add_u64 v[76:77], v[76:77], 0, v[156:157]
	v_pk_mul_f32 v[78:79], v[82:83], v[146:147] op_sel_hi:[1,0]
	v_pk_mul_f32 v[82:83], v[74:75], v[146:147] op_sel_hi:[1,0]
	v_pk_mul_f32 v[74:75], v[72:73], v[146:147] op_sel_hi:[1,0]
	v_cvt_pk_bf16_f32 v72, v80, v81
	v_cvt_pk_bf16_f32 v73, v78, v79
	v_rsq_f32_e32 v142, v142
	v_cvt_pk_bf16_f32 v74, v74, v75
	v_cvt_pk_bf16_f32 v75, v82, v83
	global_store_dwordx4 v[76:77], v[72:75], off
	v_pk_mul_f32 v[32:33], v[32:33], v[140:141] op_sel_hi:[1,0]
	v_add_u32_e32 v139, 0xb0, v138
	v_pk_mul_f32 v[72:73], v[66:67], v[146:147] op_sel_hi:[1,0]
	v_pk_mul_f32 v[66:67], v[64:65], v[146:147] op_sel_hi:[1,0]
	v_cvt_pk_bf16_f32 v64, v68, v69
	v_cvt_pk_bf16_f32 v65, v70, v71
	v_pk_mul_f32 v[22:23], v[22:23], v[140:141] op_sel_hi:[1,0]
	v_cvt_pk_bf16_f32 v66, v66, v67
	v_cvt_pk_bf16_f32 v67, v72, v73
	global_store_dwordx4 v[76:77], v[64:67], off offset:256
; __device__ __forceinline__ unsigned cvt_pk_bf16(float lo, float hi) { unsigned r; asm volatile("v_cvt_pk_bf16_f32 %0, %1, %2" : "=v"(r) : "v"(lo), "v"(hi)); return r; }
; #define PG8_BAR __builtin_amdgcn_s_barrier()
;     __device__ __forceinline__ void operator()(const f32x4 (&acc)[2][2][4][2], const Unit& u, int wr, int wc, int fr, int fq) const {
;     ...
;         for (int ai = 0; ai < 2; ++ai)
; #pragma unroll
;             for (int m = 0; m < 4; ++m) {
;                 const int row = row0 + ai * HALF + m * 16;
;                 const float rs = rsv[ai][m];
;                 bf16_t* rowp = O + (size_t)row * ldc + col0;
; #pragma unroll
;                 for (int bj = 0; bj < 2; ++bj) {
;                     const f32x4 v0 = acc[ai][bj][m][0] * rs, v1 = acc[ai][bj][m][1] * rs;
;                     u32x4 w; w.x = cvt_pk_bf16(v0[0], v0[1]); w.y = cvt_pk_bf16(v0[2], v0[3]); w.z = cvt_pk_bf16(v1[0], v1[1]); w.w = cvt_pk_bf16(v1[2], v1[3]);
;                     *(u32x4*)(rowp + bj * HALF) = w;
;                 }
;             }
; template <class Epi, class Sched, bool ALIGN_EPI = false, bool SP2 = true>
; __device__ __forceinline__ void gemm_phase(PG8_LAS unsigned char* lds, const Gemm g, const Sched& S, const Epi& E) {
;     ...
;         if constexpr (ALIGN_EPI) { if (wr == 1) PG8_BAR; }
	v_pk_mul_f32 v[20:21], v[20:21], v[140:141] op_sel_hi:[1,0]
	v_pk_mul_f32 v[16:17], v[16:17], v[142:143] op_sel_hi:[1,0]
	v_mad_i64_i32 v[64:65], s[6:7], v151, s26, 0
	v_lshl_add_u64 v[64:65], v[64:65], 1, s[62:63]
	v_lshl_add_u64 v[64:65], v[64:65], 0, v[156:157]
	v_pk_mul_f32 v[66:67], v[58:59], v[148:149] op_sel_hi:[1,0]
	v_pk_mul_f32 v[58:59], v[56:57], v[148:149] op_sel_hi:[1,0]
	v_cvt_pk_bf16_f32 v56, v60, v61
	v_cvt_pk_bf16_f32 v57, v62, v63
	v_pk_mul_f32 v[6:7], v[6:7], v[142:143] op_sel_hi:[1,0]
	v_cvt_pk_bf16_f32 v58, v58, v59
	v_cvt_pk_bf16_f32 v59, v66, v67
	global_store_dwordx4 v[64:65], v[56:59], off
	v_pk_mul_f32 v[4:5], v[4:5], v[142:143] op_sel_hi:[1,0]
	s_nop 0
	v_pk_mul_f32 v[56:57], v[46:47], v[148:149] op_sel_hi:[1,0]
	v_pk_mul_f32 v[46:47], v[44:45], v[148:149] op_sel_hi:[1,0]
	v_cvt_pk_bf16_f32 v44, v52, v53
	v_cvt_pk_bf16_f32 v45, v54, v55
	s_nop 0
	v_cvt_pk_bf16_f32 v46, v46, v47
	v_cvt_pk_bf16_f32 v47, v56, v57
	global_store_dwordx4 v[64:65], v[44:47], off offset:256
	s_nop 1
	v_add_u32_e32 v44, 0x90, v138
	v_mad_i64_i32 v[44:45], s[6:7], v44, s26, 0
	v_lshl_add_u64 v[44:45], v[44:45], 1, s[62:63]
	v_lshl_add_u64 v[44:45], v[44:45], 0, v[156:157]
	v_pk_mul_f32 v[46:47], v[50:51], v[144:145] op_sel_hi:[1,0]
	v_pk_mul_f32 v[50:51], v[42:43], v[144:145] op_sel_hi:[1,0]
	v_pk_mul_f32 v[42:43], v[40:41], v[144:145] op_sel_hi:[1,0]
	v_cvt_pk_bf16_f32 v40, v48, v49
	v_cvt_pk_bf16_f32 v41, v46, v47
	s_nop 0
	v_cvt_pk_bf16_f32 v42, v42, v43
	v_cvt_pk_bf16_f32 v43, v50, v51
	global_store_dwordx4 v[44:45], v[40:43], off
	s_nop 1
	v_pk_mul_f32 v[40:41], v[30:31], v[144:145] op_sel_hi:[1,0]
	v_pk_mul_f32 v[30:31], v[28:29], v[144:145] op_sel_hi:[1,0]
	v_cvt_pk_bf16_f32 v28, v36, v37
	v_cvt_pk_bf16_f32 v29, v38, v39
	s_nop 0
	v_cvt_pk_bf16_f32 v30, v30, v31
	v_cvt_pk_bf16_f32 v31, v40, v41
	global_store_dwordx4 v[44:45], v[28:31], off offset:256
	s_nop 1
	v_add_u32_e32 v28, 0xa0, v138
	v_mad_i64_i32 v[28:29], s[6:7], v28, s26, 0
	v_lshl_add_u64 v[28:29], v[28:29], 1, s[62:63]
	v_lshl_add_u64 v[28:29], v[28:29], 0, v[156:157]
	v_pk_mul_f32 v[30:31], v[34:35], v[140:141] op_sel_hi:[1,0]
	v_pk_mul_f32 v[34:35], v[26:27], v[140:141] op_sel_hi:[1,0]
	v_pk_mul_f32 v[26:27], v[24:25], v[140:141] op_sel_hi:[1,0]
	v_cvt_pk_bf16_f32 v24, v32, v33
	v_cvt_pk_bf16_f32 v25, v30, v31
	s_nop 0
	v_cvt_pk_bf16_f32 v26, v26, v27
	v_cvt_pk_bf16_f32 v27, v34, v35
	global_store_dwordx4 v[28:29], v[24:27], off
	s_nop 1
	v_pk_mul_f32 v[24:25], v[14:15], v[140:141] op_sel_hi:[1,0]
	v_pk_mul_f32 v[14:15], v[12:13], v[140:141] op_sel_hi:[1,0]
	v_cvt_pk_bf16_f32 v12, v20, v21
	v_cvt_pk_bf16_f32 v13, v22, v23
	s_nop 0
	v_cvt_pk_bf16_f32 v14, v14, v15
	v_cvt_pk_bf16_f32 v15, v24, v25
	global_store_dwordx4 v[28:29], v[12:15], off offset:256
	s_nop 1
	v_mad_i64_i32 v[12:13], s[6:7], v139, s26, 0
	v_lshl_add_u64 v[12:13], v[12:13], 1, s[62:63]
	v_lshl_add_u64 v[12:13], v[12:13], 0, v[156:157]
	v_pk_mul_f32 v[14:15], v[18:19], v[142:143] op_sel_hi:[1,0]
	v_pk_mul_f32 v[18:19], v[10:11], v[142:143] op_sel_hi:[1,0]
	v_pk_mul_f32 v[10:11], v[8:9], v[142:143] op_sel_hi:[1,0]
	v_cvt_pk_bf16_f32 v8, v16, v17
	v_cvt_pk_bf16_f32 v9, v14, v15
	s_nop 0
	v_cvt_pk_bf16_f32 v10, v10, v11
	v_cvt_pk_bf16_f32 v11, v18, v19
	global_store_dwordx4 v[12:13], v[8:11], off
	s_nop 1
	v_pk_mul_f32 v[8:9], v[2:3], v[142:143] op_sel_hi:[1,0]
	v_pk_mul_f32 v[2:3], v[0:1], v[142:143] op_sel_hi:[1,0]
	v_cvt_pk_bf16_f32 v0, v4, v5
	v_cvt_pk_bf16_f32 v1, v6, v7
	s_nop 0
	v_cvt_pk_bf16_f32 v2, v2, v3
	v_cvt_pk_bf16_f32 v3, v8, v9
	global_store_dwordx4 v[12:13], v[0:3], off offset:256
	s_cbranch_vccnz .LBB0_372
	s_andn2_b64 vcc, exec, s[20:21]
	s_cbranch_vccnz .LBB0_371
	s_barrier
	s_branch .LBB0_371
